# v86 + write-through (sc1) on all stores of the scan phase (YRAW, converted images, carried states) so the following grid barrier's release fence finds a clean L2
# speedup vs baseline: 1.0070x; 1.0028x over previous
.Lh_loop:
	s_cmp_eq_u32 s12, 0
	s_cbranch_scc1 .Lh_nopost
	s_add_i32 s13, s12, 1
	s_and_b32 s13, s13, 1
	s_lshl_b32 s14, s13, 12
	v_add_u32_e32 v198, s14, v195
	s_lshl_b32 s14, s13, 7
	v_add_u32_e32 v199, s14, v196
	ds_read_b128 v[200:203], v198
	ds_read_b128 v[212:215], v198 offset:12288
	s_lshl_b32 s14, s13, 8
	v_add_u32_e32 v198, s14, v197
	ds_read_b64 v[220:221], v198
	s_mul_i32 s14, s13, 0xc000
	v_add_u32_e32 v198, s14, v222
	ds_read_b128 v[216:219], v198 offset:1280
	ds_read_b32 v204, v199
	s_waitcnt lgkmcnt(0)
	v_fmac_f32_e32 v200, v212, v220
	v_fmac_f32_e32 v201, v213, v220
	v_fmac_f32_e32 v202, v214, v220
	v_fmac_f32_e32 v203, v215, v220
	v_fmac_f32_e32 v200, v216, v221
	v_fmac_f32_e32 v201, v217, v221
	v_fmac_f32_e32 v202, v218, v221
	v_fmac_f32_e32 v203, v219, v221
	v_cvt_pk_bf16_f32 v200, v200, v201
	v_cvt_pk_bf16_f32 v201, v202, v203
	global_store_dwordx2 v[190:191], v[200:201], off sc1
	s_mov_b64 s[4:5], exec
	s_and_b64 exec, exec, s[40:41]
	s_cbranch_execz .Lh_nobeta_loop
	global_store_dword v[192:193], v204, off sc1

.Lh_nopost:
	s_cmp_lt_u32 s12, 64
	s_cbranch_scc0 .Lh_nobuild
	s_add_i32 s13, s12, 1
	s_and_b32 s13, s13, 1
	s_waitcnt vmcnt(1)
	v_lshlrev_b32_e32 v84, 16, v52
	v_and_b32_e32 v85, 0xffff0000, v52
	v_lshlrev_b32_e32 v86, 16, v53
	v_and_b32_e32 v87, 0xffff0000, v53
	v_lshlrev_b32_e32 v88, 16, v54
	v_and_b32_e32 v89, 0xffff0000, v54
	v_lshlrev_b32_e32 v90, 16, v55
	v_and_b32_e32 v91, 0xffff0000, v55
	v_lshlrev_b32_e32 v124, 16, v64
	v_and_b32_e32 v125, 0xffff0000, v64
	v_lshlrev_b32_e32 v126, 16, v65
	v_and_b32_e32 v127, 0xffff0000, v65
	v_lshlrev_b32_e32 v128, 16, v66
	v_and_b32_e32 v129, 0xffff0000, v66
	v_lshlrev_b32_e32 v130, 16, v67
	v_and_b32_e32 v131, 0xffff0000, v67
	v_pk_add_f32 v[124:125], v[124:125], v[84:85] neg_lo:[0,1] neg_hi:[0,1]
	v_pk_add_f32 v[126:127], v[126:127], v[86:87] neg_lo:[0,1] neg_hi:[0,1]
	v_pk_add_f32 v[128:129], v[128:129], v[88:89] neg_lo:[0,1] neg_hi:[0,1]
	v_pk_add_f32 v[130:131], v[130:131], v[90:91] neg_lo:[0,1] neg_hi:[0,1]
	v_pk_fma_f32 v[84:85], v[0:1], v[124:125], v[84:85]
	v_pk_fma_f32 v[86:87], v[2:3], v[126:127], v[86:87]
	v_pk_fma_f32 v[88:89], v[4:5], v[128:129], v[88:89]
	v_pk_fma_f32 v[90:91], v[6:7], v[130:131], v[90:91]
	v_lshlrev_b32_e32 v92, 16, v56
	v_and_b32_e32 v93, 0xffff0000, v56
	v_lshlrev_b32_e32 v94, 16, v57
	v_and_b32_e32 v95, 0xffff0000, v57
	v_lshlrev_b32_e32 v96, 16, v58
	v_and_b32_e32 v97, 0xffff0000, v58
	v_lshlrev_b32_e32 v98, 16, v59
	v_and_b32_e32 v99, 0xffff0000, v59
	v_lshlrev_b32_e32 v124, 16, v68
	v_and_b32_e32 v125, 0xffff0000, v68
	v_lshlrev_b32_e32 v126, 16, v69
	v_and_b32_e32 v127, 0xffff0000, v69
	v_lshlrev_b32_e32 v128, 16, v70
	v_and_b32_e32 v129, 0xffff0000, v70
	v_lshlrev_b32_e32 v130, 16, v71
	v_and_b32_e32 v131, 0xffff0000, v71
	v_pk_add_f32 v[124:125], v[124:125], v[92:93] neg_lo:[0,1] neg_hi:[0,1]
	v_pk_add_f32 v[126:127], v[126:127], v[94:95] neg_lo:[0,1] neg_hi:[0,1]
	v_pk_add_f32 v[128:129], v[128:129], v[96:97] neg_lo:[0,1] neg_hi:[0,1]
	v_pk_add_f32 v[130:131], v[130:131], v[98:99] neg_lo:[0,1] neg_hi:[0,1]
	v_pk_fma_f32 v[92:93], v[8:9], v[124:125], v[92:93]
	v_pk_fma_f32 v[94:95], v[10:11], v[126:127], v[94:95]
	v_pk_fma_f32 v[96:97], v[12:13], v[128:129], v[96:97]
	v_pk_fma_f32 v[98:99], v[14:15], v[130:131], v[98:99]
	v_lshlrev_b32_e32 v100, 16, v60
	v_and_b32_e32 v101, 0xffff0000, v60
	v_lshlrev_b32_e32 v102, 16, v61
	v_and_b32_e32 v103, 0xffff0000, v61
	v_lshlrev_b32_e32 v104, 16, v62
	v_and_b32_e32 v105, 0xffff0000, v62
	v_lshlrev_b32_e32 v106, 16, v63
	v_and_b32_e32 v107, 0xffff0000, v63
	v_lshlrev_b32_e32 v124, 16, v72
	v_and_b32_e32 v125, 0xffff0000, v72
	v_lshlrev_b32_e32 v126, 16, v73
	v_and_b32_e32 v127, 0xffff0000, v73
	v_lshlrev_b32_e32 v128, 16, v74
	v_and_b32_e32 v129, 0xffff0000, v74
	v_lshlrev_b32_e32 v130, 16, v75
	v_and_b32_e32 v131, 0xffff0000, v75
	v_pk_add_f32 v[124:125], v[124:125], v[100:101] neg_lo:[0,1] neg_hi:[0,1]
	v_pk_add_f32 v[126:127], v[126:127], v[102:103] neg_lo:[0,1] neg_hi:[0,1]
	v_pk_add_f32 v[128:129], v[128:129], v[104:105] neg_lo:[0,1] neg_hi:[0,1]
	v_pk_add_f32 v[130:131], v[130:131], v[106:107] neg_lo:[0,1] neg_hi:[0,1]
	v_pk_fma_f32 v[100:101], v[16:17], v[124:125], v[100:101]
	v_pk_fma_f32 v[102:103], v[18:19], v[126:127], v[102:103]
	v_pk_fma_f32 v[104:105], v[20:21], v[128:129], v[104:105]
	v_pk_fma_f32 v[106:107], v[22:23], v[130:131], v[106:107]
	v_lshlrev_b32_e32 v108, 16, v80
	v_and_b32_e32 v109, 0xffff0000, v80
	v_lshlrev_b32_e32 v110, 16, v81
	v_and_b32_e32 v111, 0xffff0000, v81
	v_lshlrev_b32_e32 v112, 16, v82
	v_and_b32_e32 v113, 0xffff0000, v82
	v_lshlrev_b32_e32 v114, 16, v83
	v_and_b32_e32 v115, 0xffff0000, v83
	v_lshlrev_b32_e32 v116, 16, v76
	v_and_b32_e32 v117, 0xffff0000, v76
	v_lshlrev_b32_e32 v118, 16, v77
	v_and_b32_e32 v119, 0xffff0000, v77
	v_lshlrev_b32_e32 v120, 16, v78
	v_and_b32_e32 v121, 0xffff0000, v78
	v_lshlrev_b32_e32 v122, 16, v79
	v_and_b32_e32 v123, 0xffff0000, v79
	v_pk_mul_f32 v[132:133], v[92:93], v[24:25]
	v_pk_mul_f32 v[134:135], v[94:95], v[26:27]
	v_pk_mul_f32 v[136:137], v[96:97], v[28:29]
	v_pk_mul_f32 v[138:139], v[98:99], v[30:31]
	v_pk_add_f32 v[124:125], v[108:109], -1.0 op_sel_hi:[1,0]
	v_pk_add_f32 v[126:127], v[110:111], -1.0 op_sel_hi:[1,0]
	v_pk_add_f32 v[128:129], v[112:113], -1.0 op_sel_hi:[1,0]
	v_pk_add_f32 v[130:131], v[114:115], -1.0 op_sel_hi:[1,0]
	v_pk_fma_f32 v[124:125], v[32:33], v[124:125], 1.0 op_sel_hi:[1,1,0]
	v_pk_fma_f32 v[126:127], v[34:35], v[126:127], 1.0 op_sel_hi:[1,1,0]
	v_pk_fma_f32 v[128:129], v[36:37], v[128:129], 1.0 op_sel_hi:[1,1,0]
	v_pk_fma_f32 v[130:131], v[38:39], v[130:131], 1.0 op_sel_hi:[1,1,0]
	v_pk_mul_f32 v[140:141], v[124:125], v[92:93]
	v_pk_mul_f32 v[142:143], v[126:127], v[94:95]
	v_pk_mul_f32 v[144:145], v[128:129], v[96:97]
	v_pk_mul_f32 v[146:147], v[130:131], v[98:99]
	v_pk_mul_f32 v[148:149], v[84:85], v[140:141]
	v_pk_mul_f32 v[150:151], v[86:87], v[142:143]
	v_pk_mul_f32 v[152:153], v[88:89], v[144:145]
	v_pk_mul_f32 v[154:155], v[90:91], v[146:147]
	v_pk_mul_f32 v[156:157], v[132:133], v[108:109]
	v_pk_mul_f32 v[158:159], v[134:135], v[110:111]
	v_pk_mul_f32 v[160:161], v[136:137], v[112:113]
	v_pk_mul_f32 v[162:163], v[138:139], v[114:115]
	v_pk_mul_f32 v[124:125], v[148:149], v[40:41]
	v_pk_mul_f32 v[126:127], v[150:151], v[42:43]
	v_pk_mul_f32 v[128:129], v[152:153], v[44:45]
	v_pk_mul_f32 v[130:131], v[154:155], v[46:47]
	v_pk_add_f32 v[124:125], v[124:125], v[126:127]
	v_pk_add_f32 v[128:129], v[128:129], v[130:131]
	v_pk_add_f32 v[124:125], v[124:125], v[128:129]
	v_add_f32_e32 v173, v124, v125
	v_pk_mul_f32 v[124:125], v[156:157], v[84:85]
	v_pk_mul_f32 v[126:127], v[158:159], v[86:87]
	v_pk_mul_f32 v[128:129], v[160:161], v[88:89]
	v_pk_mul_f32 v[130:131], v[162:163], v[90:91]
	v_pk_add_f32 v[124:125], v[124:125], v[126:127]
	v_pk_add_f32 v[128:129], v[128:129], v[130:131]
	v_pk_add_f32 v[124:125], v[124:125], v[128:129]
	v_add_f32_e32 v174, v124, v125
	v_pk_mul_f32 v[124:125], v[132:133], v[132:133]
	v_pk_mul_f32 v[126:127], v[134:135], v[134:135]
	v_pk_mul_f32 v[128:129], v[136:137], v[136:137]
	v_pk_mul_f32 v[130:131], v[138:139], v[138:139]
	v_pk_add_f32 v[124:125], v[124:125], v[126:127]
	v_pk_add_f32 v[128:129], v[128:129], v[130:131]
	v_pk_add_f32 v[124:125], v[124:125], v[128:129]
	v_add_f32_e32 v172, v124, v125
	v_pk_add_f32 v[148:149], v[148:149], v[150:151]
	v_pk_add_f32 v[152:153], v[152:153], v[154:155]
	v_pk_add_f32 v[148:149], v[148:149], v[152:153]
	v_add_f32_e32 v175, v148, v149
	v_pk_mul_f32 v[116:117], v[116:117], v[48:49]
	v_pk_mul_f32 v[118:119], v[118:119], v[48:49]
	v_pk_mul_f32 v[120:121], v[120:121], v[48:49]
	v_pk_mul_f32 v[122:123], v[122:123], v[48:49]
	v_add_f32_dpp v172, v172, v172 quad_perm:[1,0,3,2] row_mask:0xf bank_mask:0xf bound_ctrl:1
	v_add_f32_dpp v173, v173, v173 quad_perm:[1,0,3,2] row_mask:0xf bank_mask:0xf bound_ctrl:1
	v_add_f32_dpp v174, v174, v174 quad_perm:[1,0,3,2] row_mask:0xf bank_mask:0xf bound_ctrl:1
	v_add_f32_dpp v175, v175, v175 quad_perm:[1,0,3,2] row_mask:0xf bank_mask:0xf bound_ctrl:1
	v_add_f32_dpp v172, v172, v172 quad_perm:[2,3,0,1] row_mask:0xf bank_mask:0xf bound_ctrl:1
	v_add_f32_dpp v173, v173, v173 quad_perm:[2,3,0,1] row_mask:0xf bank_mask:0xf bound_ctrl:1
	v_add_f32_dpp v174, v174, v174 quad_perm:[2,3,0,1] row_mask:0xf bank_mask:0xf bound_ctrl:1
	v_add_f32_dpp v175, v175, v175 quad_perm:[2,3,0,1] row_mask:0xf bank_mask:0xf bound_ctrl:1
	v_add_f32_dpp v172, v172, v172 row_half_mirror row_mask:0xf bank_mask:0xf bound_ctrl:1
	v_add_f32_dpp v173, v173, v173 row_half_mirror row_mask:0xf bank_mask:0xf bound_ctrl:1
	v_add_f32_dpp v174, v174, v174 row_half_mirror row_mask:0xf bank_mask:0xf bound_ctrl:1
	v_add_f32_dpp v175, v175, v175 row_half_mirror row_mask:0xf bank_mask:0xf bound_ctrl:1
	v_exp_f32_e32 v116, v116
	v_exp_f32_e32 v117, v117
	v_exp_f32_e32 v118, v118
	v_exp_f32_e32 v119, v119
	v_exp_f32_e32 v120, v120
	v_exp_f32_e32 v121, v121
	v_exp_f32_e32 v122, v122
	v_exp_f32_e32 v123, v123
	v_rsq_f32_e32 v176, v172
	v_pk_mul_f32 v[148:149], v[116:117], v[84:85]
	v_pk_mul_f32 v[150:151], v[118:119], v[86:87]
	v_pk_mul_f32 v[152:153], v[120:121], v[88:89]
	v_pk_mul_f32 v[154:155], v[122:123], v[90:91]
	v_min_f32_e32 v176, 0x5368d4a5, v176
	v_mul_f32_e32 v174, v174, v176
	v_pk_mul_f32 v[164:165], v[132:133], v[176:177] op_sel_hi:[1,0] neg_lo:[1,0] neg_hi:[1,0]
	v_pk_mul_f32 v[166:167], v[134:135], v[176:177] op_sel_hi:[1,0] neg_lo:[1,0] neg_hi:[1,0]
	v_pk_mul_f32 v[168:169], v[136:137], v[176:177] op_sel_hi:[1,0] neg_lo:[1,0] neg_hi:[1,0]
	v_pk_mul_f32 v[170:171], v[138:139], v[176:177] op_sel_hi:[1,0] neg_lo:[1,0] neg_hi:[1,0]
	v_pk_mul_f32 v[156:157], v[156:157], v[176:177] op_sel_hi:[1,0]
	v_pk_mul_f32 v[158:159], v[158:159], v[176:177] op_sel_hi:[1,0]
	v_pk_mul_f32 v[160:161], v[160:161], v[176:177] op_sel_hi:[1,0]
	v_pk_mul_f32 v[162:163], v[162:163], v[176:177] op_sel_hi:[1,0]
	s_mul_i32 s14, s13, 0xc000
	v_add_u32_e32 v198, s14, v194
	ds_write_b128 v198, v[148:151] offset:0
	ds_write_b128 v198, v[152:155] offset:128
	ds_write_b128 v198, v[116:119] offset:256
	ds_write_b128 v198, v[120:123] offset:384
	ds_write_b128 v198, v[140:143] offset:512
	ds_write_b128 v198, v[144:147] offset:640
	ds_write_b128 v198, v[164:167] offset:768
	ds_write_b128 v198, v[168:171] offset:896
	ds_write_b128 v198, v[156:159] offset:1024
	ds_write_b128 v198, v[160:163] offset:1152
	ds_write_b128 v198, v[100:103] offset:1280
	ds_write_b128 v198, v[104:107] offset:1408
	s_lshl_b32 s14, s13, 7
	v_add_u32_e32 v199, s14, v196
	s_lshl_b32 s14, s13, 8
	v_add_u32_e32 v198, s14, v197
	ds_write_b32 v199, v173
	ds_write_b64 v198, v[174:175]
	s_sub_u32 s0, s12, 1
	s_cmp_lt_u32 s0, 16
	s_cbranch_scc0 .Lhs_noproc
	s_mov_b32 s50, s0
	s_lshr_b32 s51, s50, 1
	s_and_b32 s52, s50, 1
	s_mul_i32 s53, s51, 0x600
	v_add_u32_e32 v198, s53, v238
	s_lshl_b32 s54, s52, 7
	s_add_i32 s53, s53, s54
	v_add_u32_e32 v199, s53, v239
	ds_read_b128 v[84:87], v198 offset:768
	ds_read_b128 v[88:91], v198 offset:896
	ds_read_b128 v[92:95], v198 offset:256
	ds_read_b128 v[96:99], v198 offset:384
	ds_read_b128 v[100:103], v198 offset:1024
	ds_read_b128 v[104:107], v198 offset:1152
	ds_read_b128 v[108:111], v198 offset:512
	ds_read_b128 v[112:115], v198 offset:640
	ds_read_b128 v[116:119], v198
	ds_read_b128 v[120:123], v198 offset:128
	ds_read_b32 v124, v199
	s_lshl_b32 s53, s51, 8
	s_add_i32 s53, s53, s54
	v_add_u32_e32 v205, s53, v240
	s_waitcnt lgkmcnt(0)
	v_pk_mul_f32 v[128:129], v[242:243], v[84:85]
	v_pk_fma_f32 v[128:129], v[244:245], v[86:87], v[128:129]
	v_pk_fma_f32 v[128:129], v[246:247], v[88:89], v[128:129]
	v_pk_fma_f32 v[128:129], v[248:249], v[90:91], v[128:129]
	v_add_f32_e32 v126, v128, v129
	v_pk_mul_f32 v[242:243], v[242:243], v[92:93]
	v_pk_mul_f32 v[244:245], v[244:245], v[94:95]
	v_pk_mul_f32 v[246:247], v[246:247], v[96:97]
	v_pk_mul_f32 v[248:249], v[248:249], v[98:99]
	v_add_f32_dpp v126, v126, v126 quad_perm:[1,0,3,2] row_mask:0xf bank_mask:0xf bound_ctrl:1
	s_nop 0
	s_nop 0
	v_add_f32_dpp v126, v126, v126 quad_perm:[2,3,0,1] row_mask:0xf bank_mask:0xf bound_ctrl:1
	s_nop 0
	s_nop 0
	v_add_f32_dpp v126, v126, v126 row_half_mirror row_mask:0xf bank_mask:0xf bound_ctrl:1
	v_pk_fma_f32 v[242:243], v[100:101], v[126:127], v[242:243] op_sel_hi:[1,0,1]
	v_pk_fma_f32 v[244:245], v[102:103], v[126:127], v[244:245] op_sel_hi:[1,0,1]
	v_pk_fma_f32 v[246:247], v[104:105], v[126:127], v[246:247] op_sel_hi:[1,0,1]
	v_pk_fma_f32 v[248:249], v[106:107], v[126:127], v[248:249] op_sel_hi:[1,0,1]
	v_pk_fma_f32 v[242:243], v[108:109], v[124:125], v[242:243] op_sel_hi:[1,0,1]
	v_pk_fma_f32 v[244:245], v[110:111], v[124:125], v[244:245] op_sel_hi:[1,0,1]
	v_pk_fma_f32 v[246:247], v[112:113], v[124:125], v[246:247] op_sel_hi:[1,0,1]
	v_pk_fma_f32 v[248:249], v[114:115], v[124:125], v[248:249] op_sel_hi:[1,0,1]
	v_pk_mul_f32 v[128:129], v[242:243], v[116:117]
	v_pk_fma_f32 v[128:129], v[244:245], v[118:119], v[128:129]
	v_pk_fma_f32 v[128:129], v[246:247], v[120:121], v[128:129]
	v_pk_fma_f32 v[128:129], v[248:249], v[122:123], v[128:129]
	v_add_f32_e32 v130, v128, v129
	global_store_dwordx4 v[236:237], v[242:245], off sc1
	global_store_dwordx4 v[236:237], v[246:249], off offset:128 sc1
	v_add_f32_dpp v130, v130, v130 quad_perm:[1,0,3,2] row_mask:0xf bank_mask:0xf bound_ctrl:1
	s_nop 0
	s_nop 0
	v_add_f32_dpp v130, v130, v130 quad_perm:[2,3,0,1] row_mask:0xf bank_mask:0xf bound_ctrl:1
	s_nop 0
	s_nop 0
	v_add_f32_dpp v130, v130, v130 row_half_mirror row_mask:0xf bank_mask:0xf bound_ctrl:1
	s_mov_b64 s[52:53], 0x2000
	v_lshl_add_u64 v[236:237], v[236:237], 0, s[52:53]
	ds_write_b32 v205, v130

.Lhs_noload:
	s_cmp_eq_u32 s12, 17
	s_cbranch_scc0 .Lhs_nofin
	s_cmp_lt_u32 s11, 6
	s_cbranch_scc0 .Lhs_nofin
	v_add_u32_e32 v84, 0xffffff00, v241
	v_lshrrev_b32_e32 v85, 4, v84
	v_and_b32_e32 v86, 15, v84
	v_lshlrev_b32_e32 v87, 8, v85
	v_lshl_add_u32 v87, v86, 4, v87
	v_add_u32_e32 v87, 0x1a400, v87
	v_lshlrev_b32_e32 v88, 2, v85
	v_add_u32_e32 v88, 0x1ac00, v88
	ds_read_b128 v[92:95], v87
	ds_read_b32 v96, v88
	s_lshl_b32 s50, s10, 3
	v_add_u32_e32 v89, s50, v85
	v_lshlrev_b32_e32 v90, 6, v89
	v_lshl_add_u32 v90, v86, 2, v90
	v_lshlrev_b32_e32 v90, 1, v90
	v_lshlrev_b32_e32 v91, 2, v89
	s_lshr_b32 s51, s8, 1
	s_add_i32 s51, s51, 0x4080
	s_lshl_b32 s52, s51, 11
	s_add_u32 s54, s86, 0x5700000
	s_addc_u32 s55, s87, 0
	s_add_u32 s54, s54, s52
	s_addc_u32 s55, s55, 0
	s_lshl_b32 s52, s51, 6
	s_add_u32 s56, s86, 0x7884000
	s_addc_u32 s57, s87, 0
	s_add_u32 s56, s56, s52
	s_addc_u32 s57, s57, 0
	v_cmp_eq_u32_e32 vcc, 0, v86
	s_waitcnt lgkmcnt(0)
	v_cvt_pk_bf16_f32 v92, v92, v93
	v_cvt_pk_bf16_f32 v93, v94, v95
	global_store_dwordx2 v90, v[92:93], s[54:55] sc1
	s_and_saveexec_b64 s[58:59], vcc
	global_store_dword v91, v96, s[56:57] sc1
	s_mov_b64 exec, s[58:59]

.Lcv_noscale:
	s_nop 1
	v_mov_b32_dpp v84, v242 quad_perm:[1,0,3,2] row_mask:0xf bank_mask:0xf
	v_mov_b32_dpp v85, v243 quad_perm:[1,0,3,2] row_mask:0xf bank_mask:0xf
	v_mov_b32_dpp v89, v244 quad_perm:[1,0,3,2] row_mask:0xf bank_mask:0xf
	v_mov_b32_dpp v90, v245 quad_perm:[1,0,3,2] row_mask:0xf bank_mask:0xf
	v_mov_b32_dpp v94, v246 quad_perm:[1,0,3,2] row_mask:0xf bank_mask:0xf
	v_mov_b32_dpp v95, v247 quad_perm:[1,0,3,2] row_mask:0xf bank_mask:0xf
	v_mov_b32_dpp v99, v248 quad_perm:[1,0,3,2] row_mask:0xf bank_mask:0xf
	v_mov_b32_dpp v100, v249 quad_perm:[1,0,3,2] row_mask:0xf bank_mask:0xf
	v_mov_b32_dpp v104, v236 quad_perm:[1,0,3,2] row_mask:0xf bank_mask:0xf
	v_mov_b32_dpp v105, v237 quad_perm:[1,0,3,2] row_mask:0xf bank_mask:0xf
	v_mov_b32_dpp v109, v238 quad_perm:[1,0,3,2] row_mask:0xf bank_mask:0xf
	v_mov_b32_dpp v110, v239 quad_perm:[1,0,3,2] row_mask:0xf bank_mask:0xf
	v_mov_b32_dpp v114, v224 quad_perm:[1,0,3,2] row_mask:0xf bank_mask:0xf
	v_mov_b32_dpp v115, v225 quad_perm:[1,0,3,2] row_mask:0xf bank_mask:0xf
	v_mov_b32_dpp v119, v226 quad_perm:[1,0,3,2] row_mask:0xf bank_mask:0xf
	v_mov_b32_dpp v120, v227 quad_perm:[1,0,3,2] row_mask:0xf bank_mask:0xf
	v_cndmask_b32_e64 v86, v85, v242, s[62:63]
	v_cndmask_b32_e64 v87, v243, v84, s[62:63]
	v_cvt_pk_bf16_f32 v88, v86, v87
	v_cndmask_b32_e64 v91, v90, v244, s[62:63]
	v_cndmask_b32_e64 v92, v245, v89, s[62:63]
	v_cvt_pk_bf16_f32 v93, v91, v92
	v_cndmask_b32_e64 v96, v95, v246, s[62:63]
	v_cndmask_b32_e64 v97, v247, v94, s[62:63]
	v_cvt_pk_bf16_f32 v98, v96, v97
	v_cndmask_b32_e64 v101, v100, v248, s[62:63]
	v_cndmask_b32_e64 v102, v249, v99, s[62:63]
	v_cvt_pk_bf16_f32 v103, v101, v102
	v_cndmask_b32_e64 v106, v105, v236, s[62:63]
	v_cndmask_b32_e64 v107, v237, v104, s[62:63]
	v_cvt_pk_bf16_f32 v108, v106, v107
	v_cndmask_b32_e64 v111, v110, v238, s[62:63]
	v_cndmask_b32_e64 v112, v239, v109, s[62:63]
	v_cvt_pk_bf16_f32 v113, v111, v112
	v_cndmask_b32_e64 v116, v115, v224, s[62:63]
	v_cndmask_b32_e64 v117, v225, v114, s[62:63]
	v_cvt_pk_bf16_f32 v118, v116, v117
	v_cndmask_b32_e64 v121, v120, v226, s[62:63]
	v_cndmask_b32_e64 v122, v227, v119, s[62:63]
	v_cvt_pk_bf16_f32 v123, v121, v122
	global_store_dword v232, v88, s[50:51] sc1
	s_add_u32 s50, s50, s52
	s_addc_u32 s51, s51, 0
	global_store_dword v232, v93, s[50:51] sc1
	s_add_u32 s50, s50, s52
	s_addc_u32 s51, s51, 0
	global_store_dword v232, v98, s[50:51] sc1
	s_add_u32 s50, s50, s52
	s_addc_u32 s51, s51, 0
	global_store_dword v232, v103, s[50:51] sc1
	s_add_u32 s50, s50, s52
	s_addc_u32 s51, s51, 0
	global_store_dword v232, v108, s[50:51] sc1
	s_add_u32 s50, s50, s52
	s_addc_u32 s51, s51, 0
	global_store_dword v232, v113, s[50:51] sc1
	s_add_u32 s50, s50, s52
	s_addc_u32 s51, s51, 0
	global_store_dword v232, v118, s[50:51] sc1
	s_add_u32 s50, s50, s52
	s_addc_u32 s51, s51, 0
	global_store_dword v232, v123, s[50:51] sc1

.Lh_nobuild:
	s_waitcnt lgkmcnt(0)
	s_barrier
	s_add_i32 s12, s12, 1
	s_cmp_lt_u32 s12, 0x41
	s_cbranch_scc1 .Lh_loop
	s_mov_b32 s13, 0
	s_and_saveexec_b64 s[6:7], s[28:29]
	s_cbranch_execz .Lh_post_skip_last
	s_lshl_b32 s14, s13, 12
	v_add_u32_e32 v198, s14, v195
	s_lshl_b32 s14, s13, 7
	v_add_u32_e32 v199, s14, v196
	ds_read_b128 v[200:203], v198
	ds_read_b128 v[212:215], v198 offset:12288
	s_lshl_b32 s14, s13, 8
	v_add_u32_e32 v198, s14, v197
	ds_read_b64 v[220:221], v198
	s_mul_i32 s14, s13, 0xc000
	v_add_u32_e32 v198, s14, v222
	ds_read_b128 v[216:219], v198 offset:1280
	ds_read_b32 v204, v199
	s_waitcnt lgkmcnt(0)
	v_fmac_f32_e32 v200, v212, v220
	v_fmac_f32_e32 v201, v213, v220
	v_fmac_f32_e32 v202, v214, v220
	v_fmac_f32_e32 v203, v215, v220
	v_fmac_f32_e32 v200, v216, v221
	v_fmac_f32_e32 v201, v217, v221
	v_fmac_f32_e32 v202, v218, v221
	v_fmac_f32_e32 v203, v219, v221
	v_cvt_pk_bf16_f32 v200, v200, v201
	v_cvt_pk_bf16_f32 v201, v202, v203
	global_store_dwordx2 v[190:191], v[200:201], off sc1
	s_mov_b64 s[4:5], exec
	s_and_b64 exec, exec, s[40:41]
	s_cbranch_execz .Lh_nobeta_last
	global_store_dword v[192:193], v204, off sc1

.Lrec_chunk_end:
	s_waitcnt lgkmcnt(0)
	s_barrier
	s_add_i32 s4, s4, 1
	s_cmpk_lg_i32 s4, 0x41
	s_cbranch_scc1 .Lrec_chunk
	s_lshl_b64 s[0:1], s[48:49], 4
	v_readlane_b32 s4, v255, 43
	v_readlane_b32 s5, v255, 44
	v_mov_b32_e32 v90, v0
	v_mov_b32_e32 v91, v2
	s_add_u32 s0, s0, s4
	s_addc_u32 s1, s1, s5
	s_or_b32 s0, s0, s9
	s_lshl_b64 s[0:1], s[0:1], 14
	v_readlane_b32 s4, v252, 33
	v_readlane_b32 s5, v252, 34
	v_mov_b32_e32 v92, v4
	v_mov_b32_e32 v93, v6
	v_mov_b32_e32 v94, v1
	v_mov_b32_e32 v95, v3
	s_add_u32 s0, s4, s0
	s_addc_u32 s1, s5, s1
	v_mov_b32_e32 v96, v5
	v_mov_b32_e32 v97, v7
	v_lshl_add_u32 v98, v87, 6, v86
	v_lshl_add_u32 v99, v88, 6, v86
	s_nop 1
	global_store_dwordx4 v98, v[90:93], s[0:1] sc1
	global_store_dwordx4 v99, v[94:97], s[0:1] sc1
	s_branch .LBB0_508
